# speedup vs baseline: 1.0085x; 1.0085x over previous
; DEVI void phase0(const Params& p, char* shm) {
;     ...
;     u16* abf = (u16*)(ws + OFF_ABF);
;     float* ss = (float*)(ws + OFF_SUMSQ);
;     float* lf = (float*)(ws + OFF_LF);
;     const int rstep = gridDim.x * 8;
;     int row = blockIdx.x * 8 + wid;
;     f32x4 xv[4];
;     if (row < MREAL + NMETA) {
;       const float* src = row < MREAL ? p.x + (size_t)row * DM : p.meta + (size_t)(row - MREAL) * DM;
; #pragma unroll
;       for (int i = 0; i < 4; ++i) xv[i] = __builtin_nontemporal_load(reinterpret_cast<const f32x4*>(src + lane * 4 + 256 * i));
;     }
;     while (row < MREAL + NMETA) {
;     ...
;       float dot = 0.f;
; #pragma unroll
;       for (int j = 0; j < 16; ++j) dot = (lane == j) ? acc[j] : dot;
;       if (lane < 16) {
;         int ln = lane;
;         asm volatile("" : "+v"(ln));
;         float z = dot * rstd + p.fox_b_f[ln];
.LBB0_128:
	s_or_b64 exec, exec, s[4:5]
	s_lshl_b32 s33, s2, 3
	v_add_u32_e32 v34, s33, v20
	s_mov_b32 s84, 0x8010
	s_lshl_b32 s44, s3, 3
	v_cmp_gt_i32_e32 vcc, s84, v34
	s_waitcnt lgkmcnt(0)
	s_barrier
	s_and_saveexec_b64 s[50:51], vcc
	s_cbranch_execz .LBB0_140
	s_mov_b32 s85, 0x8000
	v_add_u32_e32 v1, 0xffff8000, v34
	v_cmp_gt_i32_e32 vcc, s85, v34
	v_ashrrev_i32_e32 v35, 31, v34
	s_waitcnt vmcnt(5)
	v_mov_b32_e32 v4, s41
	v_cndmask_b32_e32 v2, v1, v34, vcc
	v_mov_b32_e32 v1, s43
	s_waitcnt vmcnt(4)
	v_cndmask_b32_e32 v3, 0, v35, vcc
	s_waitcnt vmcnt(2)
	v_cndmask_b32_e32 v5, v1, v4, vcc
	v_mov_b32_e32 v1, s42
	v_mov_b32_e32 v4, s40
	v_mov_b32_e32 v37, 0
	v_cndmask_b32_e32 v4, v1, v4, vcc
	v_lshlrev_b64 v[2:3], 12, v[2:3]
	v_lshl_add_u64 v[2:3], v[4:5], 0, v[2:3]
	v_lshlrev_b32_e32 v38, 4, v50
	v_mov_b32_e32 v39, v37
	v_lshl_add_u64 v[18:19], v[2:3], 0, v[38:39]
	global_load_dwordx4 v[2:5], v[18:19], off nt
	global_load_dwordx4 v[6:9], v[18:19], off offset:1024 nt
	global_load_dwordx4 v[10:13], v[18:19], off offset:2048 nt
	global_load_dwordx4 v[14:17], v[18:19], off offset:3072 nt
	v_mbcnt_lo_u32_b32 v1, -1, 0
	v_lshlrev_b32_e32 v18, 2, v50
	v_mbcnt_hi_u32_b32 v1, -1, v1
	s_ashr_i32 s45, s44, 31
	v_lshlrev_b64 v[42:43], 11, v[34:35]
	v_add_u32_e32 v44, s44, v34
	v_lshlrev_b32_e32 v36, 2, v18
	v_and_b32_e32 v18, 64, v1
	v_cmp_eq_u32_e64 s[0:1], 0, v50
	v_cmp_gt_u32_e64 s[38:39], 16, v50
	v_cmp_eq_u32_e64 s[4:5], 15, v50
	v_cmp_eq_u32_e64 s[6:7], 14, v50
	v_cmp_eq_u32_e64 s[8:9], 13, v50
	v_cmp_eq_u32_e64 s[10:11], 12, v50
	v_cmp_eq_u32_e64 s[12:13], 11, v50
	v_cmp_eq_u32_e64 s[14:15], 10, v50
	v_cmp_eq_u32_e64 s[16:17], 9, v50
	v_cmp_eq_u32_e64 s[18:19], 8, v50
	v_cmp_eq_u32_e64 s[20:21], 7, v50
	v_cmp_eq_u32_e64 s[22:23], 6, v50
	v_cmp_eq_u32_e64 s[24:25], 5, v50
	v_cmp_eq_u32_e64 s[26:27], 4, v50
	v_cmp_eq_u32_e64 s[28:29], 3, v50
	v_cmp_eq_u32_e64 s[30:31], 2, v50
	v_cmp_eq_u32_e64 s[34:35], 1, v50
	v_lshlrev_b64 v[40:41], 2, v[34:35]
	s_lshl_b64 s[68:69], s[44:45], 2
	v_lshl_or_b32 v42, v50, 3, v42
	s_lshl_b64 s[70:71], s[44:45], 11
	v_ashrrev_i32_e32 v45, 31, v44
	s_mov_b64 s[78:79], 0
	s_mov_b32 s86, 0x800f
	v_xor_b32_e32 v35, 1, v1
	v_add_u32_e32 v39, 64, v18
	v_xor_b32_e32 v51, 2, v1
	v_xor_b32_e32 v52, 4, v1
	v_xor_b32_e32 v53, 8, v1
	v_xor_b32_e32 v54, 16, v1
	v_xor_b32_e32 v55, 32, v1
	v_mov_b32_e32 v56, 0x358637bd
	s_mov_b32 s87, 0x800000
	s_mov_b32 s88, 0xbfb8aa3b
	s_mov_b32 s89, 0x3f2aaaab
	v_mov_b32_e32 v57, 0x3ecc95a3
	s_mov_b32 s90, 0x3f317218
	s_mov_b32 s91, 0x7f800000
	s_mov_b32 s92, 0x33800000
	s_movk_i32 s93, 0x7fff
	s_mov_b32 s94, 0x8100
	v_mov_b32_e32 v58, 0x7f800000
	v_mov_b32_e32 v59, 0x7fc00000
	v_mov_b32_e32 v60, 0xff800000
	v_and_b32_e32 v92, 15, v220
	v_lshlrev_b32_e32 v92, 2, v92
	global_load_dword v92, v92, s[52:53]
	s_branch .LBB0_131

; DEVI void phase0(const Params& p, char* shm) {
;     ...
;       float rstd = rsqrtf(s2 * (1.f / DM) + EPS);
;       if (lane == 0) { ss[row] = s2; ss[MPAD + row] = 0.f; ss[2 * MPAD + row] = 0.f; ss[3 * MPAD + row] = 0.f; ss[4 * MPAD + row] = 0.f; }
;       float dot = 0.f;
; #pragma unroll
;       for (int j = 0; j < 16; ++j) dot = (lane == j) ? acc[j] : dot;
;       if (lane < 16) {
;         int ln = lane;
;         asm volatile("" : "+v"(ln));
;         float z = dot * rstd + p.fox_b_f[ln];
;         float ls = fminf(z, 0.f) - log1pf(__expf(-fabsf(z)));
;         if (row < MREAL) {
;           int b = row >> 13, t = row & 8191;
;           lf[(size_t)(b * 16 + ln) * LP + 64 + t] = ls;
;         } else {
;           for (int b = 0; b < NB; ++b) lf[(size_t)(b * 16 + ln) * LP + 48 + mi] = ls;
;         }
;       }
.LBB0_135:
	s_or_b64 exec, exec, s[80:81]
	s_and_saveexec_b64 s[80:81], s[38:39]
	s_cbranch_execz .LBB0_130
	v_mov_b32_e32 v18, v50
	v_add_f32_e32 v20, v20, v21
	v_ashrrev_i32_e32 v19, 31, v18
	v_lshl_add_u64 v[76:77], v[18:19], 2, s[52:53]
	v_mov_b32_e32 v19, v92
	s_waitcnt lgkmcnt(13)
	v_add_f32_e32 v21, v22, v23
	v_cndmask_b32_e64 v20, v75, v20, s[34:35]
	s_waitcnt lgkmcnt(12)
	v_add_f32_e32 v22, v24, v25
	v_cndmask_b32_e64 v20, v20, v21, s[30:31]
	s_waitcnt lgkmcnt(11)
	v_add_f32_e32 v23, v26, v27
	v_cndmask_b32_e64 v20, v20, v22, s[28:29]
	s_waitcnt lgkmcnt(10)
	v_add_f32_e32 v24, v28, v29
	v_cndmask_b32_e64 v20, v20, v23, s[26:27]
	s_waitcnt lgkmcnt(9)
	v_add_f32_e32 v25, v30, v31
	v_cndmask_b32_e64 v20, v20, v24, s[24:25]
	s_waitcnt lgkmcnt(8)
	v_add_f32_e32 v26, v32, v33
	v_cndmask_b32_e64 v20, v20, v25, s[22:23]
	s_waitcnt lgkmcnt(7)
	v_add_f32_e32 v27, v47, v48
	v_fmamk_f32 v48, v74, 0x3a800000, v56
	v_cndmask_b32_e64 v20, v20, v26, s[20:21]
	s_waitcnt lgkmcnt(6)
	v_add_f32_e32 v28, v49, v61
	v_mul_f32_e32 v49, 0x4b800000, v48
	v_cmp_gt_f32_e32 vcc, s87, v48
	v_cndmask_b32_e64 v20, v20, v27, s[18:19]
	s_waitcnt lgkmcnt(5)
	v_add_f32_e32 v29, v62, v63
	v_cndmask_b32_e32 v48, v48, v49, vcc
	v_cndmask_b32_e64 v20, v20, v28, s[16:17]
	s_waitcnt lgkmcnt(4)
	v_add_f32_e32 v30, v64, v65
	v_rsq_f32_e32 v21, v48
	v_cndmask_b32_e64 v20, v20, v29, s[14:15]
	s_waitcnt lgkmcnt(3)
	v_add_f32_e32 v31, v66, v67
	v_cndmask_b32_e64 v20, v20, v30, s[12:13]
	s_waitcnt lgkmcnt(2)
	v_add_f32_e32 v32, v68, v69
	v_cndmask_b32_e64 v20, v20, v31, s[10:11]
	s_waitcnt lgkmcnt(1)
	v_add_f32_e32 v33, v70, v71
	v_cndmask_b32_e64 v20, v20, v32, s[8:9]
	s_waitcnt lgkmcnt(0)
	v_add_f32_e32 v47, v72, v73
	v_mul_f32_e32 v22, 0x45800000, v21
	v_cndmask_b32_e64 v20, v20, v33, s[6:7]
	v_cndmask_b32_e32 v21, v21, v22, vcc
	v_cndmask_b32_e64 v20, v20, v47, s[4:5]
	v_fmac_f32_e32 v19, v21, v20
	v_mul_f32_e64 v20, |v19|, s88
	v_exp_f32_e32 v22, v20
	v_min_f32_e32 v19, 0, v19
	v_add_f32_e32 v23, 1.0, v22
	v_add_f32_e32 v24, -1.0, v23
	v_frexp_mant_f32_e32 v25, v23
	v_cvt_f64_f32_e32 v[20:21], v23
	v_sub_f32_e32 v26, v24, v23
	v_frexp_exp_i32_f64_e32 v20, v[20:21]
	v_cmp_gt_f32_e32 vcc, s89, v25
	v_sub_f32_e32 v24, v22, v24
	v_add_f32_e32 v21, 1.0, v26
	v_subbrev_co_u32_e32 v20, vcc, 0, v20, vcc
	v_add_f32_e32 v21, v24, v21
	v_sub_u32_e32 v24, 0, v20
	v_cvt_f32_i32_e32 v20, v20
	v_ldexp_f32 v23, v23, v24
	v_ldexp_f32 v21, v21, v24
	v_add_f32_e32 v24, -1.0, v23
	v_add_f32_e32 v25, 1.0, v23
	v_add_f32_e32 v26, 1.0, v24
	v_add_f32_e32 v27, -1.0, v25
	v_sub_f32_e32 v26, v23, v26
	v_sub_f32_e32 v23, v23, v27
	v_mul_f32_e32 v27, 0x3f317218, v20
	v_add_f32_e32 v26, v21, v26
	v_add_f32_e32 v21, v21, v23
	v_fma_f32 v23, v20, s90, -v27
	v_add_f32_e32 v28, v24, v26
	v_add_f32_e32 v29, v25, v21
	v_fmac_f32_e32 v23, 0xb102e308, v20
	v_sub_f32_e32 v20, v28, v24
	v_sub_f32_e32 v24, v29, v25
	v_rcp_f32_e32 v25, v29
	v_add_f32_e32 v30, v27, v23
	v_sub_f32_e32 v21, v21, v24
	v_sub_f32_e32 v24, v30, v27
	v_sub_f32_e32 v23, v23, v24
	v_mul_f32_e32 v24, v28, v25
	v_sub_f32_e32 v20, v26, v20
	v_mul_f32_e32 v26, v29, v24
	v_fma_f32 v27, v24, v29, -v26
	v_fmac_f32_e32 v27, v24, v21
	v_add_f32_e32 v31, v26, v27
	v_sub_f32_e32 v32, v28, v31
	v_sub_f32_e32 v26, v31, v26
	v_sub_f32_e32 v28, v28, v32
	v_sub_f32_e32 v26, v26, v27
	v_sub_f32_e32 v27, v28, v31
	v_add_f32_e32 v20, v20, v27
	v_add_f32_e32 v20, v26, v20
	v_add_f32_e32 v26, v32, v20
	v_mul_f32_e32 v27, v25, v26
	v_sub_f32_e32 v28, v32, v26
	v_mul_f32_e32 v31, v29, v27
	v_add_f32_e32 v20, v20, v28
	v_add_f32_e32 v28, v24, v27
	v_fma_f32 v29, v27, v29, -v31
	v_sub_f32_e32 v24, v28, v24
	v_fmac_f32_e32 v29, v27, v21
	v_sub_f32_e32 v21, v27, v24
	v_add_f32_e32 v24, v31, v29
	v_sub_f32_e32 v27, v24, v31
	v_sub_f32_e32 v31, v26, v24
	v_sub_f32_e32 v26, v26, v31
	v_sub_f32_e32 v24, v26, v24
	v_sub_f32_e32 v27, v27, v29
	v_add_f32_e32 v20, v20, v24
	v_add_f32_e32 v20, v27, v20
	v_add_f32_e32 v20, v31, v20
	v_mul_f32_e32 v20, v25, v20
	v_add_f32_e32 v20, v21, v20
	v_add_f32_e32 v21, v28, v20
	v_mul_f32_e32 v24, v21, v21
	v_fmamk_f32 v27, v24, 0x3e9b6dac, v57
	v_sub_f32_e32 v25, v21, v28
	v_ldexp_f32 v26, v21, 1
	v_mul_f32_e32 v21, v21, v24
	v_fmaak_f32 v24, v24, v27, 0x3f2aaada
	v_mul_f32_e32 v21, v21, v24
	v_add_f32_e32 v24, v26, v21
	v_sub_f32_e32 v20, v20, v25
	v_sub_f32_e32 v25, v24, v26
	v_ldexp_f32 v20, v20, 1
	v_sub_f32_e32 v21, v21, v25
	v_add_f32_e32 v20, v20, v21
	v_add_f32_e32 v21, v24, v20
	v_sub_f32_e32 v24, v21, v24
	v_add_f32_e32 v25, v30, v21
	v_sub_f32_e32 v20, v20, v24
	v_sub_f32_e32 v24, v25, v30
	v_sub_f32_e32 v26, v25, v24
	v_sub_f32_e32 v21, v21, v24
	v_add_f32_e32 v24, v23, v20
	v_sub_f32_e32 v26, v30, v26
	v_sub_f32_e32 v27, v24, v23
	v_add_f32_e32 v21, v21, v26
	v_sub_f32_e32 v26, v24, v27
	v_sub_f32_e32 v20, v20, v27
	v_sub_f32_e32 v23, v23, v26
	v_add_f32_e32 v21, v24, v21
	v_add_f32_e32 v20, v20, v23
	v_add_f32_e32 v23, v25, v21
	v_sub_f32_e32 v24, v23, v25
	v_sub_f32_e32 v21, v21, v24
	v_add_f32_e32 v20, v20, v21
	v_add_f32_e32 v20, v23, v20
	v_cmp_neq_f32_e32 vcc, s91, v22
	s_nop 1
	v_cndmask_b32_e32 v20, v58, v20, vcc
	v_cmp_ngt_f32_e32 vcc, -1.0, v22
	s_nop 1
	v_cndmask_b32_e32 v20, v59, v20, vcc
	v_cmp_neq_f32_e32 vcc, -1.0, v22
	s_nop 1
	v_cndmask_b32_e32 v20, v60, v20, vcc
	v_cmp_lt_f32_e64 vcc, |v22|, s92
	s_nop 1
	v_cndmask_b32_e32 v20, v20, v22, vcc
	v_sub_f32_e32 v19, v19, v20
	v_cmp_lt_i32_e32 vcc, s93, v46
	s_and_saveexec_b64 s[82:83], vcc
	s_xor_b64 s[82:83], exec, s[82:83]
	s_cbranch_execz .LBB0_138
	v_mov_b32_e32 v47, v37
	v_lshl_add_u64 v[20:21], v[46:47], 2, s[66:67]
	v_mad_i64_i32 v[22:23], s[96:97], v18, s94, v[20:21]
	v_add_co_u32_e32 v22, vcc, 0xfffe1000, v22
	s_nop 1
	v_addc_co_u32_e32 v23, vcc, -1, v23, vcc
	global_store_dword v[22:23], v19, off offset:-3904
	v_add_u32_e32 v22, 16, v18
	v_mad_i64_i32 v[22:23], s[96:97], v22, s94, v[20:21]
	v_add_co_u32_e32 v22, vcc, 0xfffe1000, v22
	s_nop 1
	v_addc_co_u32_e32 v23, vcc, -1, v23, vcc
	global_store_dword v[22:23], v19, off offset:-3904
	v_add_u32_e32 v22, 32, v18
	v_mad_i64_i32 v[22:23], s[96:97], v22, s94, v[20:21]
	v_add_co_u32_e32 v22, vcc, 0xfffe1000, v22
	v_add_u32_e32 v18, 48, v18
	s_nop 0
	v_addc_co_u32_e32 v23, vcc, -1, v23, vcc
	v_mad_i64_i32 v[20:21], s[96:97], v18, s94, v[20:21]
	v_add_co_u32_e32 v20, vcc, 0xfffe1000, v20
	global_store_dword v[22:23], v19, off offset:-3904
	s_nop 0
	v_addc_co_u32_e32 v21, vcc, -1, v21, vcc
	global_store_dword v[20:21], v19, off offset:-3904
